# baseline (speedup 1.0000x reference)
; __device__ __forceinline__ unsigned cvt_pk_bf16(float lo, float hi) { unsigned r; asm volatile("v_cvt_pk_bf16_f32 %0, %1, %2" : "=v"(r) : "v"(lo), "v"(hi)); return r; }
; __device__ __forceinline__ unsigned pk_fp8x4(float a, float b, float c, float d) { int w = 0; w = __builtin_amdgcn_cvt_pk_fp8_f32(a, b, w, false); w = __builtin_amdgcn_cvt_pk_fp8_f32(c, d, w, true); return (unsigned)w; }
; __device__ __forceinline__ void p0_prologue(const Args& a, LAS unsigned char* lds, int tid, int G) {
;     ...
;     for (int m = gw; m < SEQ; m += NGW) {
;         const f32x4* xr = (const f32x4*)(a.x + (size_t)m * DM) + lane; u32x2* o8 = (u32x2*)(ws + WS_XB + (size_t)m * DM * 2) + lane; float s = 0.f;
; #pragma unroll
;         for (int j = 0; j < 8; ++j) { const f32x4 v = xr[64 * j]; s += (v.x * v.x + v.y * v.y) + (v.z * v.z + v.w * v.w); u32x2 w; w.x = cvt_pk_bf16(v.x, v.y); w.y = cvt_pk_bf16(v.z, v.w); o8[64 * j] = w;
;             ((unsigned*)(ws + WS_XB8 + (size_t)m * DM))[64 * j + lane] = pg8::pk_fp8x4(v.x, v.y, v.z, v.w); }
;         s = wave_sum(s); if (lane == 0) SS[m] = (pg8::ss_t)(s * pg8::SS_SCALE + 0.5f);
;     }
.LBB0_44:
	s_waitcnt lgkmcnt(0)
	global_load_dwordx4 v[24:27], v[8:9], off offset:-4096
	global_load_dwordx4 v[28:31], v[8:9], off offset:-3072
	global_load_dwordx4 v[32:35], v[8:9], off offset:-2048
	global_load_dwordx4 v[36:39], v[8:9], off offset:-1024
	global_load_dwordx4 v[40:43], v[8:9], off
	global_load_dwordx4 v[44:47], v[8:9], off offset:1024
	global_load_dwordx4 v[48:51], v[8:9], off offset:2048
	global_load_dwordx4 v[52:55], v[8:9], off offset:3072
	v_mov_b32_e32 v23, 0
	v_lshl_add_u64 v[12:13], s[26:27], 0, v[6:7]
	v_add_co_u32_e64 v12, s[4:5], s3, v12
	v_lshl_add_u64 v[14:15], s[26:27], 0, v[10:11]
	s_nop 0
	v_addc_co_u32_e64 v13, s[4:5], 0, v13, s[4:5]
	v_add_co_u32_e64 v14, s[4:5], s18, v14
	s_waitcnt vmcnt(7)
	v_cvt_pk_bf16_f32 v56, v24, v25
	v_cvt_pk_bf16_f32 v57, v26, v27
	v_cvt_pk_fp8_f32 v23, v24, v25
	v_addc_co_u32_e64 v15, s[4:5], 0, v15, s[4:5]
	v_mul_f32_e32 v25, v25, v25
	v_cvt_pk_fp8_f32 v23, v26, v27 op_sel:[0,0,1]
	v_mul_f32_e32 v27, v27, v27
	v_fmac_f32_e32 v25, v24, v24
	global_store_dwordx2 v[12:13], v[56:57], off
	global_store_dword v[14:15], v23, off
	v_mov_b32_e32 v23, 0
	s_waitcnt vmcnt(8)
	v_cvt_pk_bf16_f32 v58, v28, v29
	v_cvt_pk_bf16_f32 v59, v30, v31
	v_fmac_f32_e32 v27, v26, v26
	v_add_f32_e32 v24, v25, v27
	v_cmp_lt_i32_e64 s[4:5], v17, v16
	v_cvt_pk_fp8_f32 v23, v28, v29
	v_mul_f32_e32 v25, v29, v29
	v_mul_f32_e32 v26, v31, v31
	v_fmac_f32_e32 v25, v28, v28
	v_cvt_pk_fp8_f32 v23, v30, v31 op_sel:[0,0,1]
	v_fmac_f32_e32 v26, v30, v30
	v_add_f32_e32 v25, v25, v26
	global_store_dwordx2 v[12:13], v[58:59], off offset:512
	global_store_dword v[14:15], v23, off offset:256
	v_mov_b32_e32 v23, 0
	s_waitcnt vmcnt(9)
	v_cvt_pk_bf16_f32 v56, v32, v33
	v_cvt_pk_bf16_f32 v57, v34, v35
	v_add_f32_e32 v24, v24, v25
	v_cvt_pk_fp8_f32 v23, v32, v33
	v_mul_f32_e32 v25, v33, v33
	v_mul_f32_e32 v26, v35, v35
	v_fmac_f32_e32 v25, v32, v32
	v_cvt_pk_fp8_f32 v23, v34, v35 op_sel:[0,0,1]
	v_fmac_f32_e32 v26, v34, v34
	v_add_f32_e32 v25, v25, v26
	global_store_dwordx2 v[12:13], v[56:57], off offset:1024
	global_store_dword v[14:15], v23, off offset:512
	v_mov_b32_e32 v23, 0
	s_waitcnt vmcnt(10)
	v_cvt_pk_bf16_f32 v58, v36, v37
	v_cvt_pk_bf16_f32 v59, v38, v39
	v_add_f32_e32 v24, v24, v25
	v_cvt_pk_fp8_f32 v23, v36, v37
	v_mul_f32_e32 v25, v37, v37
	v_mul_f32_e32 v26, v39, v39
	v_fmac_f32_e32 v25, v36, v36
	v_cvt_pk_fp8_f32 v23, v38, v39 op_sel:[0,0,1]
	v_fmac_f32_e32 v26, v38, v38
	v_add_f32_e32 v25, v25, v26
	global_store_dwordx2 v[12:13], v[58:59], off offset:1536
	global_store_dword v[14:15], v23, off offset:768
	v_mov_b32_e32 v23, 0
	s_waitcnt vmcnt(11)
	v_cvt_pk_bf16_f32 v56, v40, v41
	v_cvt_pk_bf16_f32 v57, v42, v43
	v_add_f32_e32 v24, v24, v25
	v_cvt_pk_fp8_f32 v23, v40, v41
	v_mul_f32_e32 v25, v41, v41
	v_mul_f32_e32 v26, v43, v43
	v_fmac_f32_e32 v25, v40, v40
	v_cvt_pk_fp8_f32 v23, v42, v43 op_sel:[0,0,1]
	v_fmac_f32_e32 v26, v42, v42
	v_add_f32_e32 v25, v25, v26
	global_store_dwordx2 v[12:13], v[56:57], off offset:2048
	global_store_dword v[14:15], v23, off offset:1024
	v_mov_b32_e32 v23, 0
	s_waitcnt vmcnt(12)
	v_cvt_pk_bf16_f32 v58, v44, v45
	v_cvt_pk_bf16_f32 v59, v46, v47
	v_add_f32_e32 v24, v24, v25
	v_cvt_pk_fp8_f32 v23, v44, v45
	v_mul_f32_e32 v25, v45, v45
	v_mul_f32_e32 v26, v47, v47
	v_fmac_f32_e32 v25, v44, v44
	v_cvt_pk_fp8_f32 v23, v46, v47 op_sel:[0,0,1]
	v_fmac_f32_e32 v26, v46, v46
	v_add_f32_e32 v25, v25, v26
	global_store_dwordx2 v[12:13], v[58:59], off offset:2560
	global_store_dword v[14:15], v23, off offset:1280
	v_mov_b32_e32 v23, 0
	s_waitcnt vmcnt(13)
	v_cvt_pk_bf16_f32 v56, v48, v49
	v_cvt_pk_bf16_f32 v57, v50, v51
	v_add_f32_e32 v24, v24, v25
	v_cvt_pk_fp8_f32 v23, v48, v49
	v_mul_f32_e32 v25, v49, v49
	v_mul_f32_e32 v26, v51, v51
	v_fmac_f32_e32 v25, v48, v48
	v_cvt_pk_fp8_f32 v23, v50, v51 op_sel:[0,0,1]
	v_fmac_f32_e32 v26, v50, v50
	v_add_f32_e32 v25, v25, v26
	global_store_dwordx2 v[12:13], v[56:57], off offset:3072
	global_store_dword v[14:15], v23, off offset:1536
	v_add_f32_e32 v24, v24, v25
	v_cndmask_b32_e64 v23, v3, v17, s[4:5]
	v_lshlrev_b32_e32 v23, 2, v23
	v_cmp_lt_i32_e64 s[4:5], v18, v16
	s_waitcnt vmcnt(14)
	v_mul_f32_e32 v25, v53, v53
	v_mul_f32_e32 v26, v55, v55
	v_fmac_f32_e32 v25, v52, v52
	v_fmac_f32_e32 v26, v54, v54
	v_add_f32_e32 v25, v25, v26
	v_add_f32_e32 v24, v24, v25
	ds_bpermute_b32 v23, v23, v24
	v_cndmask_b32_e64 v25, v3, v18, s[4:5]
	v_lshlrev_b32_e32 v25, 2, v25
	v_cmp_lt_i32_e64 s[4:5], v19, v16
	s_waitcnt lgkmcnt(0)
	v_add_f32_e32 v23, v24, v23
	ds_bpermute_b32 v24, v25, v23
	v_cndmask_b32_e64 v25, v3, v19, s[4:5]
	v_lshlrev_b32_e32 v25, 2, v25
	v_cmp_lt_i32_e64 s[4:5], v20, v16
	s_waitcnt lgkmcnt(0)
	v_add_f32_e32 v23, v23, v24
	ds_bpermute_b32 v24, v25, v23
	v_cndmask_b32_e64 v26, v3, v20, s[4:5]
	v_lshlrev_b32_e32 v26, 2, v26
	v_cmp_lt_i32_e64 s[4:5], v21, v16
	v_mov_b32_e32 v25, 0
	s_waitcnt lgkmcnt(0)
	v_add_f32_e32 v23, v23, v24
	ds_bpermute_b32 v24, v26, v23
	v_cndmask_b32_e64 v26, v3, v21, s[4:5]
	v_lshlrev_b32_e32 v26, 2, v26
	v_cmp_lt_i32_e64 s[4:5], v22, v16
	v_cvt_pk_fp8_f32 v25, v52, v53
	s_waitcnt lgkmcnt(0)
	v_add_f32_e32 v23, v23, v24
	ds_bpermute_b32 v24, v26, v23
	v_cndmask_b32_e64 v26, v3, v22, s[4:5]
	v_cvt_pk_fp8_f32 v25, v54, v55 op_sel:[0,0,1]
	s_waitcnt lgkmcnt(0)
	v_add_f32_e32 v23, v23, v24
	v_lshlrev_b32_e32 v24, 2, v26
	ds_bpermute_b32 v24, v24, v23
	v_cvt_pk_bf16_f32 v26, v52, v53
	v_cvt_pk_bf16_f32 v27, v54, v55
	global_store_dwordx2 v[12:13], v[26:27], off offset:3584
	global_store_dword v[14:15], v25, off offset:1792
	s_and_saveexec_b64 s[4:5], vcc
	s_cbranch_execz .LBB0_43
	s_waitcnt lgkmcnt(0)
	v_add_f32_e32 v12, v23, v24
	v_fma_f32 v12, v12, s19, 0.5
	v_trunc_f32_e32 v12, v12
	v_mul_f32_e32 v13, 0x2f800000, v12
	v_floor_f32_e32 v13, v13
	v_fmac_f32_e32 v12, 0xcf800000, v13
	v_cvt_u32_f32_e32 v12, v12
	v_cvt_u32_f32_e32 v13, v13
	v_lshl_add_u64 v[14:15], s[26:27], 0, v[4:5]
	global_store_dwordx2 v[14:15], v[12:13], off
	s_branch .LBB0_43
